# v68 + P0 RMSNorm two-iteration fast path: second iteration's rows loaded into a second register set right behind the first
# baseline (speedup 1.0000x reference)
.LBB0_47:
	s_or_b64 exec, exec, s[8:9]
	s_load_dword s3, s[0:1], 0x68
	s_cmpk_gt_i32 s12, 0x3fff
	v_mbcnt_lo_u32_b32 v205, -1, 0
	v_cmp_eq_u32_e64 s[0:1], 0, v204
	s_cbranch_scc1 .LBB0_58
	v_mbcnt_hi_u32_b32 v2, -1, v205
	v_and_b32_e32 v1, 64, v2
	s_ashr_i32 s7, s6, 31
	v_add_u32_e32 v3, 64, v1
	v_xor_b32_e32 v1, 1, v2
	s_lshl_b32 s4, s54, 4
	s_mul_i32 s8, s54, 24
	s_ashr_i32 s13, s12, 31
	v_cmp_lt_i32_e32 vcc, v1, v3
	v_xor_b32_e32 v4, 2, v2
	s_ashr_i32 s5, s4, 31
	s_ashr_i32 s9, s8, 31
	s_lshl_b32 s18, s54, 5
	s_lshl_b64 s[20:21], s[6:7], 12
	s_lshl_b64 s[10:11], s[6:7], 11
	s_lshl_b64 s[14:15], s[12:13], 2
	v_cndmask_b32_e32 v1, v2, v1, vcc
	v_cmp_lt_i32_e32 vcc, v4, v3
	s_add_u32 s46, s14, 0x1980000
	s_addc_u32 s47, s15, 0
	v_cndmask_b32_e32 v4, v2, v4, vcc
	s_ashr_i32 s19, s18, 31
	v_lshlrev_b32_e32 v83, 2, v4
	v_xor_b32_e32 v4, 4, v2
	s_lshl_b64 s[28:29], s[18:19], 2
	s_lshl_b64 s[14:15], s[6:7], 2
	v_cmp_lt_i32_e32 vcc, v4, v3
	s_add_u32 s48, s46, s14
	s_addc_u32 s49, s47, s15
	v_cndmask_b32_e32 v4, v2, v4, vcc
	s_lshl_b64 s[4:5], s[4:5], 2
	v_lshlrev_b32_e32 v85, 2, v4
	v_xor_b32_e32 v4, 8, v2
	s_add_u32 s56, s46, s4
	v_cmp_lt_i32_e32 vcc, v4, v3
	s_addc_u32 s57, s47, s5
	s_lshl_b64 s[4:5], s[8:9], 2
	v_cndmask_b32_e32 v4, v2, v4, vcc
	s_add_u32 s60, s46, s4
	v_lshlrev_b32_e32 v87, 2, v4
	v_xor_b32_e32 v4, 16, v2
	s_addc_u32 s61, s47, s5
	s_lshl_b64 s[4:5], s[12:13], 12
	v_cmp_lt_i32_e32 vcc, v4, v3
	s_add_u32 s4, s36, s4
	v_lshlrev_b32_e32 v66, 4, v204
	v_cndmask_b32_e32 v4, v2, v4, vcc
	v_mov_b32_e32 v67, 0
	s_addc_u32 s5, s37, s5
	v_lshlrev_b32_e32 v88, 2, v4
	v_xor_b32_e32 v4, 32, v2
	v_lshl_add_u64 v[70:71], s[4:5], 0, v[66:67]
	s_lshl_b64 s[36:37], s[18:19], 12
	s_lshl_b64 s[4:5], s[12:13], 11
	s_lshl_b64 s[44:45], s[18:19], 11
	v_cmp_lt_i32_e32 vcc, v4, v3
	s_add_u32 s7, s10, s4
	s_addc_u32 s8, s11, s5
	v_cndmask_b32_e32 v2, v2, v4, vcc
	v_lshlrev_b32_e32 v4, 3, v204
	v_lshlrev_b32_e32 v89, 2, v2
	v_or_b32_e32 v2, s7, v4
	v_mov_b32_e32 v3, s8
	s_mov_b64 s[8:9], 0x2000400
	s_add_u32 s7, s20, s4
	v_lshl_add_u64 v[74:75], v[2:3], 0, s[8:9]
	s_addc_u32 s10, s21, s5
	v_or_b32_e32 v2, s7, v4
	s_mul_hi_i32 s7, s6, 0x1800
	s_mulk_i32 s6, 0x1800
	v_or_b32_e32 v72, s4, v4
	s_add_u32 s4, s6, s4
	v_mov_b32_e32 v73, s5
	v_mov_b32_e32 v3, s10
	s_addc_u32 s5, s7, s5
	v_lshl_add_u64 v[76:77], v[2:3], 0, s[8:9]
	v_or_b32_e32 v2, s4, v4
	v_mov_b32_e32 v3, s5
	v_lshlrev_b32_e32 v1, 2, v1
	v_lshl_add_u64 v[68:69], s[38:39], 0, v[66:67]
	v_lshl_add_u64 v[78:79], v[2:3], 0, s[8:9]
	v_mov_b32_e32 v90, 0x358637bd
	s_mov_b32 s13, 0xf800000
	v_mov_b32_e32 v91, 0x260
	s_movk_i32 s19, 0x7fff
	s_mov_b32 s62, 0xffff0000
	s_brev_b32 s63, 64
	global_load_dwordx4 v[120:123], v[68:69], off
	global_load_dwordx4 v[124:127], v[68:69], off offset:1024
	global_load_dwordx4 v[128:131], v[68:69], off offset:2048
	global_load_dwordx4 v[132:135], v[68:69], off offset:3072
	s_mov_b32 s80, 0
	s_add_i32 s81, s12, s18
	s_cmpk_gt_i32 s81, 0x3fff
	s_cbranch_scc1 .Lmy_rB_noflag
	s_add_i32 s81, s81, s18
	s_cmpk_gt_i32 s81, 0x3fff
	s_cbranch_scc0 .Lmy_rB_noflag
	s_mov_b32 s80, 1
.Lmy_rB_noflag:
	s_branch .LBB0_50
.LBB0_49:
	s_or_b64 exec, exec, s[4:5]
	v_mov_b64_e32 v[92:93], v[120:121]
	v_mov_b64_e32 v[94:95], v[122:123]
	v_div_scale_f32 v96, s[4:5], v66, v66, 1.0
	v_div_scale_f32 v98, s[4:5], v82, v82, 1.0
	v_rcp_f32_e32 v104, v96
	v_div_scale_f32 v100, s[6:7], v84, v84, 1.0
	v_rcp_f32_e32 v105, v98
	v_div_scale_f32 v102, s[8:9], v86, v86, 1.0
	v_rcp_f32_e32 v106, v100
	v_rcp_f32_e32 v107, v102
	v_fma_f32 v108, -v96, v104, 1.0
	v_div_scale_f32 v97, vcc, 1.0, v66, 1.0
	v_fma_f32 v109, -v98, v105, 1.0
	v_fmac_f32_e32 v104, v108, v104
	v_div_scale_f32 v99, s[4:5], 1.0, v82, 1.0
	v_fma_f32 v110, -v100, v106, 1.0
	v_fmac_f32_e32 v105, v109, v105
	v_mul_f32_e32 v108, v97, v104
	v_div_scale_f32 v101, s[6:7], 1.0, v84, 1.0
	v_fma_f32 v111, -v102, v107, 1.0
	v_fmac_f32_e32 v106, v110, v106
	v_mul_f32_e32 v109, v99, v105
	v_fma_f32 v112, -v96, v108, v97
	v_div_scale_f32 v103, s[8:9], 1.0, v86, 1.0
	v_fmac_f32_e32 v107, v111, v107
	v_mul_f32_e32 v110, v101, v106
	v_fma_f32 v113, -v98, v109, v99
	v_fmac_f32_e32 v108, v112, v104
	v_mul_f32_e32 v111, v103, v107
	v_fma_f32 v114, -v100, v110, v101
	v_fmac_f32_e32 v109, v113, v105
	v_fma_f32 v96, -v96, v108, v97
	v_fma_f32 v115, -v102, v111, v103
	v_fmac_f32_e32 v110, v114, v106
	v_fma_f32 v97, -v98, v109, v99
	v_div_fmas_f32 v96, v96, v104, v108
	s_mov_b64 vcc, s[4:5]
	v_fmac_f32_e32 v111, v115, v107
	v_fma_f32 v98, -v100, v110, v101
	v_div_fixup_f32 v66, v96, v66, 1.0
	v_div_fmas_f32 v96, v97, v105, v109
	s_mov_b64 vcc, s[6:7]
	v_fma_f32 v99, -v102, v111, v103
	v_div_fixup_f32 v82, v96, v82, 1.0
	v_div_fmas_f32 v96, v98, v106, v110
	s_mov_b64 vcc, s[8:9]
	v_div_fixup_f32 v84, v96, v84, 1.0
	v_div_fmas_f32 v96, v99, v107, v111
	v_div_fixup_f32 v86, v96, v86, 1.0
	v_pk_mul_f32 v[58:59], v[58:59], v[86:87] op_sel_hi:[1,0]
	v_pk_mul_f32 v[60:61], v[60:61], v[86:87] op_sel_hi:[1,0]
	v_lshl_add_u64 v[80:81], s[52:53], 0, v[72:73]
	v_pk_mul_f32 v[62:63], v[62:63], v[84:85] op_sel_hi:[1,0]
	v_add_co_u32_e64 v80, s[10:11], s63, v80
	v_pk_mul_f32 v[64:65], v[64:65], v[84:85] op_sel_hi:[1,0]
	s_nop 0
	v_addc_co_u32_e64 v81, s[10:11], 0, v81, s[10:11]
	v_pk_mul_f32 v[54:55], v[54:55], v[82:83] op_sel_hi:[1,0]
	v_pk_mul_f32 v[56:57], v[56:57], v[82:83] op_sel_hi:[1,0]
	v_pk_mul_f32 v[50:51], v[50:51], v[66:67] op_sel_hi:[1,0]
	v_pk_mul_f32 v[52:53], v[52:53], v[66:67] op_sel_hi:[1,0]
	v_pk_mul_f32 v[38:39], v[38:39], v[86:87] op_sel_hi:[1,0]
	v_pk_mul_f32 v[40:41], v[40:41], v[86:87] op_sel_hi:[1,0]
	v_pk_mul_f32 v[42:43], v[42:43], v[84:85] op_sel_hi:[1,0]
	v_pk_mul_f32 v[44:45], v[44:45], v[84:85] op_sel_hi:[1,0]
	v_pk_mul_f32 v[46:47], v[46:47], v[82:83] op_sel_hi:[1,0]
	v_pk_mul_f32 v[48:49], v[48:49], v[82:83] op_sel_hi:[1,0]
	v_pk_mul_f32 v[34:35], v[34:35], v[66:67] op_sel_hi:[1,0]
	v_pk_mul_f32 v[36:37], v[36:37], v[66:67] op_sel_hi:[1,0]
	v_pk_mul_f32 v[18:19], v[18:19], v[86:87] op_sel_hi:[1,0]
	v_pk_mul_f32 v[20:21], v[20:21], v[86:87] op_sel_hi:[1,0]
	v_pk_mul_f32 v[30:31], v[30:31], v[66:67] op_sel_hi:[1,0]
	v_pk_mul_f32 v[60:61], v[60:61], v[94:95]
	v_pk_mul_f32 v[58:59], v[58:59], v[92:93]
	v_bfe_u32 v98, v60, 16, 1
	v_bfe_u32 v96, v58, 16, 1
	v_bfe_u32 v97, v59, 16, 1
	v_bfe_u32 v99, v61, 16, 1
	v_add3_u32 v58, v58, v96, s19
	v_add3_u32 v60, v60, v98, s19
	v_pk_mul_f32 v[62:63], v[62:63], v[92:93]
	v_add3_u32 v59, v59, v97, s19
	v_add3_u32 v61, v61, v99, s19
	v_lshrrev_b32_e32 v58, 16, v58
	v_lshrrev_b32_e32 v60, 16, v60
	v_bfe_u32 v100, v62, 16, 1
	v_and_or_b32 v58, v59, s62, v58
	v_and_or_b32 v59, v61, s62, v60
	v_add3_u32 v62, v62, v100, s19
	global_store_dwordx2 v[80:81], v[58:59], off
	v_bfe_u32 v58, v63, 16, 1
	v_pk_mul_f32 v[64:65], v[64:65], v[94:95]
	v_lshrrev_b32_e32 v62, 16, v62
	v_add3_u32 v58, v63, v58, s19
	v_and_or_b32 v60, v58, s62, v62
	v_bfe_u32 v58, v64, 16, 1
	v_add3_u32 v58, v64, v58, s19
	v_bfe_u32 v59, v65, 16, 1
	v_lshrrev_b32_e32 v58, 16, v58
	v_add3_u32 v59, v65, v59, s19
	v_and_or_b32 v61, v59, s62, v58
	v_lshl_add_u64 v[58:59], s[52:53], 0, v[74:75]
	v_pk_mul_f32 v[54:55], v[54:55], v[92:93]
	global_store_dwordx2 v[58:59], v[60:61], off offset:-1024
	v_bfe_u32 v60, v54, 16, 1
	v_add3_u32 v54, v54, v60, s19
	v_bfe_u32 v60, v55, 16, 1
	v_pk_mul_f32 v[56:57], v[56:57], v[94:95]
	v_lshrrev_b32_e32 v54, 16, v54
	v_add3_u32 v55, v55, v60, s19
	v_and_or_b32 v60, v55, s62, v54
	v_bfe_u32 v54, v56, 16, 1
	v_pk_mul_f32 v[50:51], v[50:51], v[92:93]
	v_add3_u32 v54, v56, v54, s19
	v_bfe_u32 v56, v50, 16, 1
	v_add3_u32 v50, v50, v56, s19
	v_bfe_u32 v56, v51, 16, 1
	v_pk_mul_f32 v[52:53], v[52:53], v[94:95]
	v_lshrrev_b32_e32 v50, 16, v50
	v_add3_u32 v51, v51, v56, s19
	v_and_or_b32 v56, v51, s62, v50
	v_bfe_u32 v50, v52, 16, 1
	v_bfe_u32 v55, v57, 16, 1
	v_add3_u32 v50, v52, v50, s19
	v_bfe_u32 v51, v53, 16, 1
	v_lshrrev_b32_e32 v54, 16, v54
	v_add3_u32 v55, v57, v55, s19
	v_lshrrev_b32_e32 v50, 16, v50
	v_add3_u32 v51, v53, v51, s19
	v_and_or_b32 v61, v55, s62, v54
	v_lshl_add_u64 v[54:55], s[52:53], 0, v[76:77]
	v_and_or_b32 v57, v51, s62, v50
	v_lshl_add_u64 v[50:51], s[52:53], 0, v[78:79]
	global_store_dwordx2 v[54:55], v[60:61], off offset:-1024
	global_store_dwordx2 v[50:51], v[56:57], off offset:-1024
	s_nop 1
	v_mov_b64_e32 v[60:61], v[124:125]
	v_mov_b64_e32 v[62:63], v[126:127]
	v_pk_mul_f32 v[32:33], v[32:33], v[66:67] op_sel_hi:[1,0]
	v_pk_mul_f32 v[26:27], v[26:27], v[82:83] op_sel_hi:[1,0]
	v_pk_mul_f32 v[28:29], v[28:29], v[82:83] op_sel_hi:[1,0]
	v_pk_mul_f32 v[22:23], v[22:23], v[84:85] op_sel_hi:[1,0]
	v_pk_mul_f32 v[24:25], v[24:25], v[84:85] op_sel_hi:[1,0]
	s_add_i32 s12, s12, s18
	s_add_u32 s46, s46, s28
	s_addc_u32 s47, s47, s29
	s_add_u32 s48, s48, s28
	v_pk_mul_f32 v[2:3], v[2:3], v[86:87] op_sel_hi:[1,0]
	v_pk_mul_f32 v[4:5], v[4:5], v[86:87] op_sel_hi:[1,0]
	s_addc_u32 s49, s49, s29
	v_pk_mul_f32 v[14:15], v[14:15], v[66:67] op_sel_hi:[1,0]
	v_pk_mul_f32 v[16:17], v[16:17], v[66:67] op_sel_hi:[1,0]
	v_pk_mul_f32 v[10:11], v[10:11], v[82:83] op_sel_hi:[1,0]
	v_pk_mul_f32 v[12:13], v[12:13], v[82:83] op_sel_hi:[1,0]
	v_pk_mul_f32 v[6:7], v[6:7], v[84:85] op_sel_hi:[1,0]
	v_pk_mul_f32 v[8:9], v[8:9], v[84:85] op_sel_hi:[1,0]
	s_add_u32 s56, s56, s28
	s_addc_u32 s57, s57, s29
	s_add_u32 s60, s60, s28
	s_addc_u32 s61, s61, s29
	v_lshl_add_u64 v[70:71], v[70:71], 0, s[36:37]
	v_lshl_add_u64 v[72:73], v[72:73], 0, s[44:45]
	v_lshl_add_u64 v[74:75], v[74:75], 0, s[44:45]
	v_lshl_add_u64 v[76:77], v[76:77], 0, s[44:45]
	s_cmpk_gt_i32 s12, 0x3fff
	v_lshl_add_u64 v[78:79], v[78:79], 0, s[44:45]
	v_pk_mul_f32 v[40:41], v[40:41], v[62:63]
	v_pk_mul_f32 v[38:39], v[38:39], v[60:61]
	v_pk_mul_f32 v[44:45], v[44:45], v[62:63]
	v_pk_mul_f32 v[42:43], v[42:43], v[60:61]
	v_bfe_u32 v52, v38, 16, 1
	v_bfe_u32 v56, v40, 16, 1
	v_bfe_u32 v53, v39, 16, 1
	v_bfe_u32 v57, v41, 16, 1
	v_bfe_u32 v64, v42, 16, 1
	v_bfe_u32 v92, v44, 16, 1
	v_add3_u32 v38, v38, v52, s19
	v_add3_u32 v40, v40, v56, s19
	v_bfe_u32 v65, v43, 16, 1
	v_bfe_u32 v93, v45, 16, 1
	v_add3_u32 v39, v39, v53, s19
	v_add3_u32 v41, v41, v57, s19
	v_add3_u32 v42, v42, v64, s19
	v_add3_u32 v44, v44, v92, s19
	v_lshrrev_b32_e32 v38, 16, v38
	v_lshrrev_b32_e32 v40, 16, v40
	v_pk_mul_f32 v[46:47], v[46:47], v[60:61]
	v_add3_u32 v43, v43, v65, s19
	v_add3_u32 v45, v45, v93, s19
	v_lshrrev_b32_e32 v42, 16, v42
	v_lshrrev_b32_e32 v44, 16, v44
	v_and_or_b32 v38, v39, s62, v38
	v_and_or_b32 v39, v41, s62, v40
	v_and_or_b32 v40, v43, s62, v42
	v_and_or_b32 v41, v45, s62, v44
	global_store_dwordx2 v[80:81], v[38:39], off offset:512
	global_store_dwordx2 v[58:59], v[40:41], off offset:-512
	v_bfe_u32 v38, v46, 16, 1
	v_add3_u32 v38, v46, v38, s19
	v_bfe_u32 v39, v47, 16, 1
	v_pk_mul_f32 v[48:49], v[48:49], v[62:63]
	v_lshrrev_b32_e32 v38, 16, v38
	v_add3_u32 v39, v47, v39, s19
	v_and_or_b32 v38, v39, s62, v38
	v_bfe_u32 v39, v48, 16, 1
	v_add3_u32 v39, v48, v39, s19
	v_bfe_u32 v40, v49, 16, 1
	v_lshrrev_b32_e32 v39, 16, v39
	v_add3_u32 v40, v49, v40, s19
	v_and_or_b32 v39, v40, s62, v39
	v_pk_mul_f32 v[34:35], v[34:35], v[60:61]
	global_store_dwordx2 v[54:55], v[38:39], off offset:-512
	v_bfe_u32 v38, v34, 16, 1
	v_add3_u32 v34, v34, v38, s19
	v_bfe_u32 v38, v35, 16, 1
	v_pk_mul_f32 v[36:37], v[36:37], v[62:63]
	v_lshrrev_b32_e32 v34, 16, v34
	v_add3_u32 v35, v35, v38, s19
	v_and_or_b32 v34, v35, s62, v34
	v_bfe_u32 v35, v36, 16, 1
	v_add3_u32 v35, v36, v35, s19
	v_bfe_u32 v36, v37, 16, 1
	v_lshrrev_b32_e32 v35, 16, v35
	v_add3_u32 v36, v37, v36, s19
	v_and_or_b32 v35, v36, s62, v35
	global_store_dwordx2 v[50:51], v[34:35], off offset:-512
	s_nop 1
	v_mov_b64_e32 v[34:35], v[128:129]
	v_mov_b64_e32 v[36:37], v[130:131]
	v_pk_mul_f32 v[20:21], v[20:21], v[36:37]
	v_pk_mul_f32 v[18:19], v[18:19], v[34:35]
	v_pk_mul_f32 v[24:25], v[24:25], v[36:37]
	v_pk_mul_f32 v[22:23], v[22:23], v[34:35]
	v_pk_mul_f32 v[28:29], v[28:29], v[36:37]
	v_pk_mul_f32 v[26:27], v[26:27], v[34:35]
	v_pk_mul_f32 v[32:33], v[32:33], v[36:37]
	v_pk_mul_f32 v[30:31], v[30:31], v[34:35]
	v_bfe_u32 v34, v18, 16, 1
	v_bfe_u32 v36, v20, 16, 1
	v_bfe_u32 v35, v19, 16, 1
	v_bfe_u32 v37, v21, 16, 1
	v_bfe_u32 v38, v22, 16, 1
	v_bfe_u32 v40, v24, 16, 1
	v_bfe_u32 v42, v26, 16, 1
	v_bfe_u32 v44, v28, 16, 1
	v_add3_u32 v18, v18, v34, s19
	v_add3_u32 v20, v20, v36, s19
	v_bfe_u32 v39, v23, 16, 1
	v_bfe_u32 v41, v25, 16, 1
	v_bfe_u32 v43, v27, 16, 1
	v_bfe_u32 v45, v29, 16, 1
	v_add3_u32 v19, v19, v35, s19
	v_add3_u32 v21, v21, v37, s19
	v_add3_u32 v22, v22, v38, s19
	v_add3_u32 v24, v24, v40, s19
	v_add3_u32 v26, v26, v42, s19
	v_add3_u32 v28, v28, v44, s19
	v_lshrrev_b32_e32 v18, 16, v18
	v_lshrrev_b32_e32 v20, 16, v20
	v_add3_u32 v23, v23, v39, s19
	v_add3_u32 v25, v25, v41, s19
	v_add3_u32 v27, v27, v43, s19
	v_add3_u32 v29, v29, v45, s19
	v_lshrrev_b32_e32 v22, 16, v22
	v_lshrrev_b32_e32 v24, 16, v24
	v_lshrrev_b32_e32 v26, 16, v26
	v_lshrrev_b32_e32 v28, 16, v28
	v_and_or_b32 v18, v19, s62, v18
	v_and_or_b32 v19, v21, s62, v20
	v_and_or_b32 v20, v23, s62, v22
	v_and_or_b32 v21, v25, s62, v24
	v_and_or_b32 v22, v27, s62, v26
	v_and_or_b32 v23, v29, s62, v28
	global_store_dwordx2 v[80:81], v[18:19], off offset:1024
	global_store_dwordx2 v[58:59], v[20:21], off
	global_store_dwordx2 v[54:55], v[22:23], off
	v_bfe_u32 v18, v30, 16, 1
	v_add3_u32 v18, v30, v18, s19
	v_bfe_u32 v19, v31, 16, 1
	v_lshrrev_b32_e32 v18, 16, v18
	v_add3_u32 v19, v31, v19, s19
	v_and_or_b32 v18, v19, s62, v18
	v_bfe_u32 v19, v32, 16, 1
	v_add3_u32 v19, v32, v19, s19
	v_bfe_u32 v20, v33, 16, 1
	v_lshrrev_b32_e32 v19, 16, v19
	v_add3_u32 v20, v33, v20, s19
	v_and_or_b32 v19, v20, s62, v19
	global_store_dwordx2 v[50:51], v[18:19], off
	s_nop 1
	v_mov_b64_e32 v[18:19], v[132:133]
	v_mov_b64_e32 v[20:21], v[134:135]
	v_pk_mul_f32 v[4:5], v[4:5], v[20:21]
	v_pk_mul_f32 v[2:3], v[2:3], v[18:19]
	v_pk_mul_f32 v[8:9], v[8:9], v[20:21]
	v_pk_mul_f32 v[6:7], v[6:7], v[18:19]
	v_pk_mul_f32 v[12:13], v[12:13], v[20:21]
	v_pk_mul_f32 v[10:11], v[10:11], v[18:19]
	v_pk_mul_f32 v[16:17], v[16:17], v[20:21]
	v_pk_mul_f32 v[14:15], v[14:15], v[18:19]
	v_bfe_u32 v18, v2, 16, 1
	v_bfe_u32 v20, v4, 16, 1
	v_bfe_u32 v19, v3, 16, 1
	v_bfe_u32 v21, v5, 16, 1
	v_bfe_u32 v22, v6, 16, 1
	v_bfe_u32 v24, v8, 16, 1
	v_bfe_u32 v26, v10, 16, 1
	v_bfe_u32 v28, v12, 16, 1
	v_bfe_u32 v30, v14, 16, 1
	v_bfe_u32 v32, v16, 16, 1
	v_add3_u32 v2, v2, v18, s19
	v_add3_u32 v4, v4, v20, s19
	v_bfe_u32 v23, v7, 16, 1
	v_bfe_u32 v25, v9, 16, 1
	v_bfe_u32 v27, v11, 16, 1
	v_bfe_u32 v29, v13, 16, 1
	v_bfe_u32 v31, v15, 16, 1
	v_bfe_u32 v33, v17, 16, 1
	v_add3_u32 v3, v3, v19, s19
	v_add3_u32 v5, v5, v21, s19
	v_add3_u32 v6, v6, v22, s19
	v_add3_u32 v8, v8, v24, s19
	v_add3_u32 v10, v10, v26, s19
	v_add3_u32 v12, v12, v28, s19
	v_add3_u32 v14, v14, v30, s19
	v_add3_u32 v16, v16, v32, s19
	v_lshrrev_b32_e32 v2, 16, v2
	v_lshrrev_b32_e32 v4, 16, v4
	v_add3_u32 v7, v7, v23, s19
	v_add3_u32 v9, v9, v25, s19
	v_add3_u32 v11, v11, v27, s19
	v_add3_u32 v13, v13, v29, s19
	v_add3_u32 v15, v15, v31, s19
	v_add3_u32 v17, v17, v33, s19
	v_lshrrev_b32_e32 v6, 16, v6
	v_lshrrev_b32_e32 v8, 16, v8
	v_lshrrev_b32_e32 v10, 16, v10
	v_lshrrev_b32_e32 v12, 16, v12
	v_lshrrev_b32_e32 v14, 16, v14
	v_lshrrev_b32_e32 v16, 16, v16
	v_and_or_b32 v2, v3, s62, v2
	v_and_or_b32 v3, v5, s62, v4
	v_and_or_b32 v4, v7, s62, v6
	v_and_or_b32 v5, v9, s62, v8
	v_and_or_b32 v6, v11, s62, v10
	v_and_or_b32 v7, v13, s62, v12
	v_and_or_b32 v8, v15, s62, v14
	v_and_or_b32 v9, v17, s62, v16
	global_store_dwordx2 v[80:81], v[2:3], off offset:1536
	global_store_dwordx2 v[58:59], v[4:5], off offset:512
	global_store_dwordx2 v[54:55], v[6:7], off offset:512
	global_store_dwordx2 v[50:51], v[8:9], off offset:512
	s_cbranch_scc1 .LBB0_58
.LBB0_50:
	s_cmp_eq_u32 s80, 2
	s_cbranch_scc1 .Lmy_rB_C
	global_load_dwordx4 v[58:61], v[70:71], off nt
	global_load_dwordx4 v[38:41], v[70:71], off offset:1024 nt
	global_load_dwordx4 v[18:21], v[70:71], off offset:2048 nt
	global_load_dwordx4 v[2:5], v[70:71], off offset:3072 nt
	v_lshl_add_u64 v[10:11], v[70:71], 0, s[20:21]
	v_lshl_add_u64 v[14:15], v[10:11], 0, s[20:21]
	global_load_dwordx4 v[62:65], v[10:11], off nt
	global_load_dwordx4 v[42:45], v[10:11], off offset:1024 nt
	global_load_dwordx4 v[22:25], v[10:11], off offset:2048 nt
	global_load_dwordx4 v[6:9], v[10:11], off offset:3072 nt
	global_load_dwordx4 v[54:57], v[14:15], off nt
	global_load_dwordx4 v[46:49], v[14:15], off offset:1024 nt
	global_load_dwordx4 v[26:29], v[14:15], off offset:2048 nt
	s_nop 0
	global_load_dwordx4 v[10:13], v[14:15], off offset:3072 nt
	v_lshl_add_u64 v[14:15], v[14:15], 0, s[20:21]
	global_load_dwordx4 v[50:53], v[14:15], off nt
	global_load_dwordx4 v[34:37], v[14:15], off offset:1024 nt
	global_load_dwordx4 v[30:33], v[14:15], off offset:2048 nt
	s_nop 0
	global_load_dwordx4 v[14:17], v[14:15], off offset:3072 nt
	s_cmp_eq_u32 s80, 1
	s_cbranch_scc0 .Lmy_rB_skipL
	v_lshl_add_u64 v[116:117], v[70:71], 0, s[36:37]
	global_load_dwordx4 v[192:195], v[116:117], off nt
	global_load_dwordx4 v[172:175], v[116:117], off offset:1024 nt
	global_load_dwordx4 v[152:155], v[116:117], off offset:2048 nt
	global_load_dwordx4 v[136:139], v[116:117], off offset:3072 nt
	v_lshl_add_u64 v[116:117], v[116:117], 0, s[20:21]
	global_load_dwordx4 v[206:209], v[116:117], off nt
	global_load_dwordx4 v[176:179], v[116:117], off offset:1024 nt
	global_load_dwordx4 v[156:159], v[116:117], off offset:2048 nt
	global_load_dwordx4 v[140:143], v[116:117], off offset:3072 nt
	v_lshl_add_u64 v[116:117], v[116:117], 0, s[20:21]
	global_load_dwordx4 v[188:191], v[116:117], off nt
	global_load_dwordx4 v[180:183], v[116:117], off offset:1024 nt
	global_load_dwordx4 v[160:163], v[116:117], off offset:2048 nt
	global_load_dwordx4 v[144:147], v[116:117], off offset:3072 nt
	v_lshl_add_u64 v[116:117], v[116:117], 0, s[20:21]
	global_load_dwordx4 v[184:187], v[116:117], off nt
	global_load_dwordx4 v[168:171], v[116:117], off offset:1024 nt
	global_load_dwordx4 v[164:167], v[116:117], off offset:2048 nt
	global_load_dwordx4 v[148:151], v[116:117], off offset:3072 nt
	s_mov_b32 s80, 2
	s_branch .Lmy_rA_C
.Lmy_rB_skipL:
	s_waitcnt vmcnt(15)
	v_mul_f32_e32 v66, v59, v59
	v_mul_f32_e32 v80, v61, v61
	s_waitcnt vmcnt(14)
	v_mul_f32_e32 v81, v39, v39
	v_mul_f32_e32 v82, v41, v41
	s_waitcnt vmcnt(13)
	v_mul_f32_e32 v84, v19, v19
	v_mul_f32_e32 v86, v21, v21
	v_fmac_f32_e32 v66, v58, v58
	v_fmac_f32_e32 v80, v60, v60
	v_fmac_f32_e32 v81, v38, v38
	v_fmac_f32_e32 v82, v40, v40
	s_waitcnt vmcnt(12)
	v_mul_f32_e32 v92, v3, v3
	v_mul_f32_e32 v93, v5, v5
	v_fmac_f32_e32 v84, v18, v18
	v_fmac_f32_e32 v86, v20, v20
	v_add_f32_e32 v66, v66, v80
	v_add_f32_e32 v80, v81, v82
	v_fmac_f32_e32 v92, v2, v2
	v_fmac_f32_e32 v93, v4, v4
	v_add_f32_e32 v81, v84, v86
	v_add_f32_e32 v66, v66, v80
	v_add_f32_e32 v82, v92, v93
	v_add_f32_e32 v66, v66, v81
	v_add_f32_e32 v66, v66, v82
	s_nop 1
	v_add_f32_dpp v66, v66, v66 row_ror:8 row_mask:0xf bank_mask:0xf
	s_nop 1
	v_add_f32_dpp v66, v66, v66 row_ror:4 row_mask:0xf bank_mask:0xf
	s_nop 1
	v_add_f32_dpp v66, v66, v66 row_ror:2 row_mask:0xf bank_mask:0xf
	s_nop 1
	v_add_f32_dpp v66, v66, v66 row_ror:1 row_mask:0xf bank_mask:0xf
	s_nop 1
	v_add_f32_dpp v66, v66, v66 row_bcast:15 row_mask:0xa bank_mask:0xf
	s_nop 1
	v_add_f32_dpp v66, v66, v66 row_bcast:31 row_mask:0xc bank_mask:0xf
	s_nop 1
	v_readlane_b32 s4, v66, 63
	s_nop 1
	v_mov_b32_e32 v66, s4
	v_fmamk_f32 v66, v66, 0x3a800000, v90
	v_mul_f32_e32 v80, 0x4f800000, v66
	v_cmp_gt_f32_e32 vcc, s13, v66
	s_nop 1
	v_cndmask_b32_e32 v66, v66, v80, vcc
	v_sqrt_f32_e32 v80, v66
	s_nop 0
	v_add_u32_e32 v81, -1, v80
	v_add_u32_e32 v82, 1, v80
	v_fma_f32 v84, -v81, v80, v66
	v_fma_f32 v86, -v82, v80, v66
	v_cmp_ge_f32_e64 s[4:5], 0, v84
	s_nop 1
	v_cndmask_b32_e64 v80, v80, v81, s[4:5]
	v_cmp_lt_f32_e64 s[4:5], 0, v86
	s_nop 1
	v_cndmask_b32_e64 v80, v80, v82, s[4:5]
	v_mul_f32_e32 v81, 0x37800000, v80
	v_cndmask_b32_e32 v80, v80, v81, vcc
	v_cmp_class_f32_e32 vcc, v66, v91
	s_nop 1
	v_cndmask_b32_e32 v86, v80, v66, vcc
	s_and_saveexec_b64 s[4:5], s[0:1]
	s_cbranch_execz .LBB0_52
	s_add_u32 s6, s52, s46
	s_addc_u32 s7, s53, s47
	global_store_dword v67, v86, s[6:7]

.Lmy_rA_C:
	s_waitcnt vmcnt(31)
	v_mul_f32_e32 v66, v59, v59
	v_mul_f32_e32 v80, v61, v61
	s_waitcnt vmcnt(30)
	v_mul_f32_e32 v81, v39, v39
	v_mul_f32_e32 v82, v41, v41
	s_waitcnt vmcnt(29)
	v_mul_f32_e32 v84, v19, v19
	v_mul_f32_e32 v86, v21, v21
	v_fmac_f32_e32 v66, v58, v58
	v_fmac_f32_e32 v80, v60, v60
	v_fmac_f32_e32 v81, v38, v38
	v_fmac_f32_e32 v82, v40, v40
	s_waitcnt vmcnt(28)
	v_mul_f32_e32 v92, v3, v3
	v_mul_f32_e32 v93, v5, v5
	v_fmac_f32_e32 v84, v18, v18
	v_fmac_f32_e32 v86, v20, v20
	v_add_f32_e32 v66, v66, v80
	v_add_f32_e32 v80, v81, v82
	v_fmac_f32_e32 v92, v2, v2
	v_fmac_f32_e32 v93, v4, v4
	v_add_f32_e32 v81, v84, v86
	v_add_f32_e32 v66, v66, v80
	v_add_f32_e32 v82, v92, v93
	v_add_f32_e32 v66, v66, v81
	v_add_f32_e32 v66, v66, v82
	s_nop 1
	v_add_f32_dpp v66, v66, v66 row_ror:8 row_mask:0xf bank_mask:0xf
	s_nop 1
	v_add_f32_dpp v66, v66, v66 row_ror:4 row_mask:0xf bank_mask:0xf
	s_nop 1
	v_add_f32_dpp v66, v66, v66 row_ror:2 row_mask:0xf bank_mask:0xf
	s_nop 1
	v_add_f32_dpp v66, v66, v66 row_ror:1 row_mask:0xf bank_mask:0xf
	s_nop 1
	v_add_f32_dpp v66, v66, v66 row_bcast:15 row_mask:0xa bank_mask:0xf
	s_nop 1
	v_add_f32_dpp v66, v66, v66 row_bcast:31 row_mask:0xc bank_mask:0xf
	s_nop 1
	v_readlane_b32 s4, v66, 63
	s_nop 1
	v_mov_b32_e32 v66, s4
	v_fmamk_f32 v66, v66, 0x3a800000, v90
	v_mul_f32_e32 v80, 0x4f800000, v66
	v_cmp_gt_f32_e32 vcc, s13, v66
	s_nop 1
	v_cndmask_b32_e32 v66, v66, v80, vcc
	v_sqrt_f32_e32 v80, v66
	s_nop 0
	v_add_u32_e32 v81, -1, v80
	v_add_u32_e32 v82, 1, v80
	v_fma_f32 v84, -v81, v80, v66
	v_fma_f32 v86, -v82, v80, v66
	v_cmp_ge_f32_e64 s[4:5], 0, v84
	s_nop 1
	v_cndmask_b32_e64 v80, v80, v81, s[4:5]
	v_cmp_lt_f32_e64 s[4:5], 0, v86
	s_nop 1
	v_cndmask_b32_e64 v80, v80, v82, s[4:5]
	v_mul_f32_e32 v81, 0x37800000, v80
	v_cndmask_b32_e32 v80, v80, v81, vcc
	v_cmp_class_f32_e32 vcc, v66, v91
	s_nop 1
	v_cndmask_b32_e32 v86, v80, v66, vcc
	s_and_saveexec_b64 s[4:5], s[0:1]
	s_cbranch_execz .Lmy_rA_52
	s_add_u32 s6, s52, s46
	s_addc_u32 s7, s53, s47
	global_store_dword v67, v86, s[6:7]
.Lmy_rA_52:
	s_or_b64 exec, exec, s[4:5]
	s_waitcnt vmcnt(27)
	v_mul_f32_e32 v66, v63, v63
	v_mul_f32_e32 v80, v65, v65
	v_fmac_f32_e32 v66, v62, v62
	v_fmac_f32_e32 v80, v64, v64
	v_add_f32_e32 v66, v66, v80
	s_waitcnt vmcnt(26)
	v_mul_f32_e32 v80, v43, v43
	v_mul_f32_e32 v81, v45, v45
	v_fmac_f32_e32 v80, v42, v42
	v_fmac_f32_e32 v81, v44, v44
	v_add_f32_e32 v80, v80, v81
	v_add_f32_e32 v66, v66, v80
	s_waitcnt vmcnt(25)
	v_mul_f32_e32 v80, v23, v23
	v_mul_f32_e32 v81, v25, v25
	v_fmac_f32_e32 v80, v22, v22
	v_fmac_f32_e32 v81, v24, v24
	v_add_f32_e32 v80, v80, v81
	v_add_f32_e32 v66, v66, v80
	s_waitcnt vmcnt(24)
	v_mul_f32_e32 v80, v7, v7
	v_mul_f32_e32 v81, v9, v9
	v_fmac_f32_e32 v80, v6, v6
	v_fmac_f32_e32 v81, v8, v8
	v_add_f32_e32 v80, v80, v81
	v_add_f32_e32 v66, v66, v80
	s_nop 1
	v_add_f32_dpp v66, v66, v66 row_ror:8 row_mask:0xf bank_mask:0xf
	s_nop 1
	v_add_f32_dpp v66, v66, v66 row_ror:4 row_mask:0xf bank_mask:0xf
	s_nop 1
	v_add_f32_dpp v66, v66, v66 row_ror:2 row_mask:0xf bank_mask:0xf
	s_nop 1
	v_add_f32_dpp v66, v66, v66 row_ror:1 row_mask:0xf bank_mask:0xf
	s_nop 1
	v_add_f32_dpp v66, v66, v66 row_bcast:15 row_mask:0xa bank_mask:0xf
	s_nop 1
	v_add_f32_dpp v66, v66, v66 row_bcast:31 row_mask:0xc bank_mask:0xf
	s_nop 1
	v_readlane_b32 s4, v66, 63
	s_nop 1
	v_mov_b32_e32 v66, s4
	v_fmamk_f32 v66, v66, 0x3a800000, v90
	v_mul_f32_e32 v80, 0x4f800000, v66
	v_cmp_gt_f32_e32 vcc, s13, v66
	s_nop 1
	v_cndmask_b32_e32 v66, v66, v80, vcc
	v_sqrt_f32_e32 v80, v66
	s_nop 0
	v_add_u32_e32 v81, -1, v80
	v_add_u32_e32 v82, 1, v80
	v_fma_f32 v84, -v81, v80, v66
	v_fma_f32 v92, -v82, v80, v66
	v_cmp_ge_f32_e64 s[4:5], 0, v84
	s_nop 1
	v_cndmask_b32_e64 v80, v80, v81, s[4:5]
	v_cmp_lt_f32_e64 s[4:5], 0, v92
	s_nop 1
	v_cndmask_b32_e64 v80, v80, v82, s[4:5]
	v_mul_f32_e32 v81, 0x37800000, v80
	v_cndmask_b32_e32 v80, v80, v81, vcc
	v_cmp_class_f32_e32 vcc, v66, v91
	s_nop 1
	v_cndmask_b32_e32 v84, v80, v66, vcc
	s_and_saveexec_b64 s[4:5], s[0:1]
	s_cbranch_execz .Lmy_rA_54
	s_add_u32 s6, s52, s48
	s_addc_u32 s7, s53, s49
	global_store_dword v67, v84, s[6:7]
.Lmy_rA_54:
	s_or_b64 exec, exec, s[4:5]
	s_waitcnt vmcnt(23)
	v_mul_f32_e32 v66, v55, v55
	v_mul_f32_e32 v80, v57, v57
	v_fmac_f32_e32 v66, v54, v54
	v_fmac_f32_e32 v80, v56, v56
	v_add_f32_e32 v66, v66, v80
	s_waitcnt vmcnt(22)
	v_mul_f32_e32 v80, v47, v47
	v_mul_f32_e32 v81, v49, v49
	v_fmac_f32_e32 v80, v46, v46
	v_fmac_f32_e32 v81, v48, v48
	v_add_f32_e32 v80, v80, v81
	v_add_f32_e32 v66, v66, v80
	s_waitcnt vmcnt(21)
	v_mul_f32_e32 v80, v27, v27
	v_mul_f32_e32 v81, v29, v29
	v_fmac_f32_e32 v80, v26, v26
	v_fmac_f32_e32 v81, v28, v28
	v_add_f32_e32 v80, v80, v81
	v_add_f32_e32 v66, v66, v80
	s_waitcnt vmcnt(20)
	v_mul_f32_e32 v80, v11, v11
	v_mul_f32_e32 v81, v13, v13
	v_fmac_f32_e32 v80, v10, v10
	v_fmac_f32_e32 v81, v12, v12
	v_add_f32_e32 v80, v80, v81
	v_add_f32_e32 v66, v66, v80
	s_nop 1
	v_add_f32_dpp v66, v66, v66 row_ror:8 row_mask:0xf bank_mask:0xf
	s_nop 1
	v_add_f32_dpp v66, v66, v66 row_ror:4 row_mask:0xf bank_mask:0xf
	s_nop 1
	v_add_f32_dpp v66, v66, v66 row_ror:2 row_mask:0xf bank_mask:0xf
	s_nop 1
	v_add_f32_dpp v66, v66, v66 row_ror:1 row_mask:0xf bank_mask:0xf
	s_nop 1
	v_add_f32_dpp v66, v66, v66 row_bcast:15 row_mask:0xa bank_mask:0xf
	s_nop 1
	v_add_f32_dpp v66, v66, v66 row_bcast:31 row_mask:0xc bank_mask:0xf
	s_nop 1
	v_readlane_b32 s4, v66, 63
	s_nop 1
	v_mov_b32_e32 v66, s4
	v_fmamk_f32 v66, v66, 0x3a800000, v90
	v_mul_f32_e32 v80, 0x4f800000, v66
	v_cmp_gt_f32_e32 vcc, s13, v66
	s_nop 1
	v_cndmask_b32_e32 v66, v66, v80, vcc
	v_sqrt_f32_e32 v80, v66
	s_nop 0
	v_add_u32_e32 v81, -1, v80
	v_add_u32_e32 v82, 1, v80
	v_fma_f32 v92, -v81, v80, v66
	v_fma_f32 v93, -v82, v80, v66
	v_cmp_ge_f32_e64 s[4:5], 0, v92
	s_nop 1
	v_cndmask_b32_e64 v80, v80, v81, s[4:5]
	v_cmp_lt_f32_e64 s[4:5], 0, v93
	s_nop 1
	v_cndmask_b32_e64 v80, v80, v82, s[4:5]
	v_mul_f32_e32 v81, 0x37800000, v80
	v_cndmask_b32_e32 v80, v80, v81, vcc
	v_cmp_class_f32_e32 vcc, v66, v91
	s_nop 1
	v_cndmask_b32_e32 v82, v80, v66, vcc
	s_and_saveexec_b64 s[4:5], s[0:1]
	s_cbranch_execz .Lmy_rA_56
	s_add_u32 s6, s52, s56
	s_addc_u32 s7, s53, s57
	global_store_dword v67, v82, s[6:7]
.Lmy_rA_56:
	s_or_b64 exec, exec, s[4:5]
	s_waitcnt vmcnt(19)
	v_mul_f32_e32 v66, v51, v51
	v_mul_f32_e32 v80, v53, v53
	v_fmac_f32_e32 v66, v50, v50
	v_fmac_f32_e32 v80, v52, v52
	v_add_f32_e32 v66, v66, v80
	s_waitcnt vmcnt(18)
	v_mul_f32_e32 v80, v35, v35
	v_mul_f32_e32 v81, v37, v37
	v_fmac_f32_e32 v80, v34, v34
	v_fmac_f32_e32 v81, v36, v36
	v_add_f32_e32 v80, v80, v81
	v_add_f32_e32 v66, v66, v80
	s_waitcnt vmcnt(17)
	v_mul_f32_e32 v80, v31, v31
	v_mul_f32_e32 v81, v33, v33
	v_fmac_f32_e32 v80, v30, v30
	v_fmac_f32_e32 v81, v32, v32
	v_add_f32_e32 v80, v80, v81
	v_add_f32_e32 v66, v66, v80
	s_waitcnt vmcnt(16)
	v_mul_f32_e32 v80, v15, v15
	v_mul_f32_e32 v81, v17, v17
	v_fmac_f32_e32 v80, v14, v14
	v_fmac_f32_e32 v81, v16, v16
	v_add_f32_e32 v80, v80, v81
	v_add_f32_e32 v66, v66, v80
	s_nop 1
	v_add_f32_dpp v66, v66, v66 row_ror:8 row_mask:0xf bank_mask:0xf
	s_nop 1
	v_add_f32_dpp v66, v66, v66 row_ror:4 row_mask:0xf bank_mask:0xf
	s_nop 1
	v_add_f32_dpp v66, v66, v66 row_ror:2 row_mask:0xf bank_mask:0xf
	s_nop 1
	v_add_f32_dpp v66, v66, v66 row_ror:1 row_mask:0xf bank_mask:0xf
	s_nop 1
	v_add_f32_dpp v66, v66, v66 row_bcast:15 row_mask:0xa bank_mask:0xf
	s_nop 1
	v_add_f32_dpp v66, v66, v66 row_bcast:31 row_mask:0xc bank_mask:0xf
	s_nop 1
	v_readlane_b32 s4, v66, 63
	s_nop 1
	v_mov_b32_e32 v66, s4
	v_fmamk_f32 v66, v66, 0x3a800000, v90
	v_mul_f32_e32 v80, 0x4f800000, v66
	v_cmp_gt_f32_e32 vcc, s13, v66
	s_nop 1
	v_cndmask_b32_e32 v66, v66, v80, vcc
	v_sqrt_f32_e32 v80, v66
	s_nop 0
	v_add_u32_e32 v81, -1, v80
	v_add_u32_e32 v92, 1, v80
	v_fma_f32 v93, -v81, v80, v66
	v_fma_f32 v94, -v92, v80, v66
	v_cmp_ge_f32_e64 s[4:5], 0, v93
	s_nop 1
	v_cndmask_b32_e64 v80, v80, v81, s[4:5]
	v_cmp_lt_f32_e64 s[4:5], 0, v94
	s_nop 1
	v_cndmask_b32_e64 v80, v80, v92, s[4:5]
	v_mul_f32_e32 v81, 0x37800000, v80
	v_cndmask_b32_e32 v80, v80, v81, vcc
	v_cmp_class_f32_e32 vcc, v66, v91
	s_nop 1
	v_cndmask_b32_e32 v66, v80, v66, vcc
	s_and_saveexec_b64 s[4:5], s[0:1]
	s_cbranch_execz .LBB0_49
	s_add_u32 s6, s52, s60
	s_addc_u32 s7, s53, s61
	global_store_dword v67, v66, s[6:7]
	s_branch .LBB0_49
.Lmy_rB_C:
	s_waitcnt vmcnt(15)
	v_mul_f32_e32 v66, v193, v193
	v_mul_f32_e32 v80, v195, v195
	s_waitcnt vmcnt(14)
	v_mul_f32_e32 v81, v173, v173
	v_mul_f32_e32 v82, v175, v175
	s_waitcnt vmcnt(13)
	v_mul_f32_e32 v84, v153, v153
	v_mul_f32_e32 v86, v155, v155
	v_fmac_f32_e32 v66, v192, v192
	v_fmac_f32_e32 v80, v194, v194
	v_fmac_f32_e32 v81, v172, v172
	v_fmac_f32_e32 v82, v174, v174
	s_waitcnt vmcnt(12)
	v_mul_f32_e32 v92, v137, v137
	v_mul_f32_e32 v93, v139, v139
	v_fmac_f32_e32 v84, v152, v152
	v_fmac_f32_e32 v86, v154, v154
	v_add_f32_e32 v66, v66, v80
	v_add_f32_e32 v80, v81, v82
	v_fmac_f32_e32 v92, v136, v136
	v_fmac_f32_e32 v93, v138, v138
	v_add_f32_e32 v81, v84, v86
	v_add_f32_e32 v66, v66, v80
	v_add_f32_e32 v82, v92, v93
	v_add_f32_e32 v66, v66, v81
	v_add_f32_e32 v66, v66, v82
	s_nop 1
	v_add_f32_dpp v66, v66, v66 row_ror:8 row_mask:0xf bank_mask:0xf
	s_nop 1
	v_add_f32_dpp v66, v66, v66 row_ror:4 row_mask:0xf bank_mask:0xf
	s_nop 1
	v_add_f32_dpp v66, v66, v66 row_ror:2 row_mask:0xf bank_mask:0xf
	s_nop 1
	v_add_f32_dpp v66, v66, v66 row_ror:1 row_mask:0xf bank_mask:0xf
	s_nop 1
	v_add_f32_dpp v66, v66, v66 row_bcast:15 row_mask:0xa bank_mask:0xf
	s_nop 1
	v_add_f32_dpp v66, v66, v66 row_bcast:31 row_mask:0xc bank_mask:0xf
	s_nop 1
	v_readlane_b32 s4, v66, 63
	s_nop 1
	v_mov_b32_e32 v66, s4
	v_fmamk_f32 v66, v66, 0x3a800000, v90
	v_mul_f32_e32 v80, 0x4f800000, v66
	v_cmp_gt_f32_e32 vcc, s13, v66
	s_nop 1
	v_cndmask_b32_e32 v66, v66, v80, vcc
	v_sqrt_f32_e32 v80, v66
	s_nop 0
	v_add_u32_e32 v81, -1, v80
	v_add_u32_e32 v82, 1, v80
	v_fma_f32 v84, -v81, v80, v66
	v_fma_f32 v86, -v82, v80, v66
	v_cmp_ge_f32_e64 s[4:5], 0, v84
	s_nop 1
	v_cndmask_b32_e64 v80, v80, v81, s[4:5]
	v_cmp_lt_f32_e64 s[4:5], 0, v86
	s_nop 1
	v_cndmask_b32_e64 v80, v80, v82, s[4:5]
	v_mul_f32_e32 v81, 0x37800000, v80
	v_cndmask_b32_e32 v80, v80, v81, vcc
	v_cmp_class_f32_e32 vcc, v66, v91
	s_nop 1
	v_cndmask_b32_e32 v86, v80, v66, vcc
	s_and_saveexec_b64 s[4:5], s[0:1]
	s_cbranch_execz .Lmy_rB_52
	s_add_u32 s6, s52, s46
	s_addc_u32 s7, s53, s47
	global_store_dword v67, v86, s[6:7]
.Lmy_rB_52:
	s_or_b64 exec, exec, s[4:5]
	s_waitcnt vmcnt(11)
	v_mul_f32_e32 v66, v207, v207
	v_mul_f32_e32 v80, v209, v209
	v_fmac_f32_e32 v66, v206, v206
	v_fmac_f32_e32 v80, v208, v208
	v_add_f32_e32 v66, v66, v80
	s_waitcnt vmcnt(10)
	v_mul_f32_e32 v80, v177, v177
	v_mul_f32_e32 v81, v179, v179
	v_fmac_f32_e32 v80, v176, v176
	v_fmac_f32_e32 v81, v178, v178
	v_add_f32_e32 v80, v80, v81
	v_add_f32_e32 v66, v66, v80
	s_waitcnt vmcnt(9)
	v_mul_f32_e32 v80, v157, v157
	v_mul_f32_e32 v81, v159, v159
	v_fmac_f32_e32 v80, v156, v156
	v_fmac_f32_e32 v81, v158, v158
	v_add_f32_e32 v80, v80, v81
	v_add_f32_e32 v66, v66, v80
	s_waitcnt vmcnt(8)
	v_mul_f32_e32 v80, v141, v141
	v_mul_f32_e32 v81, v143, v143
	v_fmac_f32_e32 v80, v140, v140
	v_fmac_f32_e32 v81, v142, v142
	v_add_f32_e32 v80, v80, v81
	v_add_f32_e32 v66, v66, v80
	s_nop 1
	v_add_f32_dpp v66, v66, v66 row_ror:8 row_mask:0xf bank_mask:0xf
	s_nop 1
	v_add_f32_dpp v66, v66, v66 row_ror:4 row_mask:0xf bank_mask:0xf
	s_nop 1
	v_add_f32_dpp v66, v66, v66 row_ror:2 row_mask:0xf bank_mask:0xf
	s_nop 1
	v_add_f32_dpp v66, v66, v66 row_ror:1 row_mask:0xf bank_mask:0xf
	s_nop 1
	v_add_f32_dpp v66, v66, v66 row_bcast:15 row_mask:0xa bank_mask:0xf
	s_nop 1
	v_add_f32_dpp v66, v66, v66 row_bcast:31 row_mask:0xc bank_mask:0xf
	s_nop 1
	v_readlane_b32 s4, v66, 63
	s_nop 1
	v_mov_b32_e32 v66, s4
	v_fmamk_f32 v66, v66, 0x3a800000, v90
	v_mul_f32_e32 v80, 0x4f800000, v66
	v_cmp_gt_f32_e32 vcc, s13, v66
	s_nop 1
	v_cndmask_b32_e32 v66, v66, v80, vcc
	v_sqrt_f32_e32 v80, v66
	s_nop 0
	v_add_u32_e32 v81, -1, v80
	v_add_u32_e32 v82, 1, v80
	v_fma_f32 v84, -v81, v80, v66
	v_fma_f32 v92, -v82, v80, v66
	v_cmp_ge_f32_e64 s[4:5], 0, v84
	s_nop 1
	v_cndmask_b32_e64 v80, v80, v81, s[4:5]
	v_cmp_lt_f32_e64 s[4:5], 0, v92
	s_nop 1
	v_cndmask_b32_e64 v80, v80, v82, s[4:5]
	v_mul_f32_e32 v81, 0x37800000, v80
	v_cndmask_b32_e32 v80, v80, v81, vcc
	v_cmp_class_f32_e32 vcc, v66, v91
	s_nop 1
	v_cndmask_b32_e32 v84, v80, v66, vcc
	s_and_saveexec_b64 s[4:5], s[0:1]
	s_cbranch_execz .Lmy_rB_54
	s_add_u32 s6, s52, s48
	s_addc_u32 s7, s53, s49
	global_store_dword v67, v84, s[6:7]
.Lmy_rB_54:
	s_or_b64 exec, exec, s[4:5]
	s_waitcnt vmcnt(7)
	v_mul_f32_e32 v66, v189, v189
	v_mul_f32_e32 v80, v191, v191
	v_fmac_f32_e32 v66, v188, v188
	v_fmac_f32_e32 v80, v190, v190
	v_add_f32_e32 v66, v66, v80
	s_waitcnt vmcnt(6)
	v_mul_f32_e32 v80, v181, v181
	v_mul_f32_e32 v81, v183, v183
	v_fmac_f32_e32 v80, v180, v180
	v_fmac_f32_e32 v81, v182, v182
	v_add_f32_e32 v80, v80, v81
	v_add_f32_e32 v66, v66, v80
	s_waitcnt vmcnt(5)
	v_mul_f32_e32 v80, v161, v161
	v_mul_f32_e32 v81, v163, v163
	v_fmac_f32_e32 v80, v160, v160
	v_fmac_f32_e32 v81, v162, v162
	v_add_f32_e32 v80, v80, v81
	v_add_f32_e32 v66, v66, v80
	s_waitcnt vmcnt(4)
	v_mul_f32_e32 v80, v145, v145
	v_mul_f32_e32 v81, v147, v147
	v_fmac_f32_e32 v80, v144, v144
	v_fmac_f32_e32 v81, v146, v146
	v_add_f32_e32 v80, v80, v81
	v_add_f32_e32 v66, v66, v80
	s_nop 1
	v_add_f32_dpp v66, v66, v66 row_ror:8 row_mask:0xf bank_mask:0xf
	s_nop 1
	v_add_f32_dpp v66, v66, v66 row_ror:4 row_mask:0xf bank_mask:0xf
	s_nop 1
	v_add_f32_dpp v66, v66, v66 row_ror:2 row_mask:0xf bank_mask:0xf
	s_nop 1
	v_add_f32_dpp v66, v66, v66 row_ror:1 row_mask:0xf bank_mask:0xf
	s_nop 1
	v_add_f32_dpp v66, v66, v66 row_bcast:15 row_mask:0xa bank_mask:0xf
	s_nop 1
	v_add_f32_dpp v66, v66, v66 row_bcast:31 row_mask:0xc bank_mask:0xf
	s_nop 1
	v_readlane_b32 s4, v66, 63
	s_nop 1
	v_mov_b32_e32 v66, s4
	v_fmamk_f32 v66, v66, 0x3a800000, v90
	v_mul_f32_e32 v80, 0x4f800000, v66
	v_cmp_gt_f32_e32 vcc, s13, v66
	s_nop 1
	v_cndmask_b32_e32 v66, v66, v80, vcc
	v_sqrt_f32_e32 v80, v66
	s_nop 0
	v_add_u32_e32 v81, -1, v80
	v_add_u32_e32 v82, 1, v80
	v_fma_f32 v92, -v81, v80, v66
	v_fma_f32 v93, -v82, v80, v66
	v_cmp_ge_f32_e64 s[4:5], 0, v92
	s_nop 1
	v_cndmask_b32_e64 v80, v80, v81, s[4:5]
	v_cmp_lt_f32_e64 s[4:5], 0, v93
	s_nop 1
	v_cndmask_b32_e64 v80, v80, v82, s[4:5]
	v_mul_f32_e32 v81, 0x37800000, v80
	v_cndmask_b32_e32 v80, v80, v81, vcc
	v_cmp_class_f32_e32 vcc, v66, v91
	s_nop 1
	v_cndmask_b32_e32 v82, v80, v66, vcc
	s_and_saveexec_b64 s[4:5], s[0:1]
	s_cbranch_execz .Lmy_rB_56
	s_add_u32 s6, s52, s56
	s_addc_u32 s7, s53, s57
	global_store_dword v67, v82, s[6:7]
.Lmy_rB_56:
	s_or_b64 exec, exec, s[4:5]
	s_waitcnt vmcnt(3)
	v_mul_f32_e32 v66, v185, v185
	v_mul_f32_e32 v80, v187, v187
	v_fmac_f32_e32 v66, v184, v184
	v_fmac_f32_e32 v80, v186, v186
	v_add_f32_e32 v66, v66, v80
	s_waitcnt vmcnt(2)
	v_mul_f32_e32 v80, v169, v169
	v_mul_f32_e32 v81, v171, v171
	v_fmac_f32_e32 v80, v168, v168
	v_fmac_f32_e32 v81, v170, v170
	v_add_f32_e32 v80, v80, v81
	v_add_f32_e32 v66, v66, v80
	s_waitcnt vmcnt(1)
	v_mul_f32_e32 v80, v165, v165
	v_mul_f32_e32 v81, v167, v167
	v_fmac_f32_e32 v80, v164, v164
	v_fmac_f32_e32 v81, v166, v166
	v_add_f32_e32 v80, v80, v81
	v_add_f32_e32 v66, v66, v80
	s_waitcnt vmcnt(0)
	v_mul_f32_e32 v80, v149, v149
	v_mul_f32_e32 v81, v151, v151
	v_fmac_f32_e32 v80, v148, v148
	v_fmac_f32_e32 v81, v150, v150
	v_add_f32_e32 v80, v80, v81
	v_add_f32_e32 v66, v66, v80
	s_nop 1
	v_add_f32_dpp v66, v66, v66 row_ror:8 row_mask:0xf bank_mask:0xf
	s_nop 1
	v_add_f32_dpp v66, v66, v66 row_ror:4 row_mask:0xf bank_mask:0xf
	s_nop 1
	v_add_f32_dpp v66, v66, v66 row_ror:2 row_mask:0xf bank_mask:0xf
	s_nop 1
	v_add_f32_dpp v66, v66, v66 row_ror:1 row_mask:0xf bank_mask:0xf
	s_nop 1
	v_add_f32_dpp v66, v66, v66 row_bcast:15 row_mask:0xa bank_mask:0xf
	s_nop 1
	v_add_f32_dpp v66, v66, v66 row_bcast:31 row_mask:0xc bank_mask:0xf
	s_nop 1
	v_readlane_b32 s4, v66, 63
	s_nop 1
	v_mov_b32_e32 v66, s4
	v_fmamk_f32 v66, v66, 0x3a800000, v90
	v_mul_f32_e32 v80, 0x4f800000, v66
	v_cmp_gt_f32_e32 vcc, s13, v66
	s_nop 1
	v_cndmask_b32_e32 v66, v66, v80, vcc
	v_sqrt_f32_e32 v80, v66
	s_nop 0
	v_add_u32_e32 v81, -1, v80
	v_add_u32_e32 v92, 1, v80
	v_fma_f32 v93, -v81, v80, v66
	v_fma_f32 v94, -v92, v80, v66
	v_cmp_ge_f32_e64 s[4:5], 0, v93
	s_nop 1
	v_cndmask_b32_e64 v80, v80, v81, s[4:5]
	v_cmp_lt_f32_e64 s[4:5], 0, v94
	s_nop 1
	v_cndmask_b32_e64 v80, v80, v92, s[4:5]
	v_mul_f32_e32 v81, 0x37800000, v80
	v_cndmask_b32_e32 v80, v80, v81, vcc
	v_cmp_class_f32_e32 vcc, v66, v91
	s_nop 1
	v_cndmask_b32_e32 v66, v80, v66, vcc
	s_and_saveexec_b64 s[4:5], s[0:1]
	s_cbranch_execz .Lmy_rB_S
	s_add_u32 s6, s52, s60
	s_addc_u32 s7, s53, s61
	global_store_dword v67, v66, s[6:7]
	s_branch .Lmy_rB_S
.Lmy_rB_S:
	s_or_b64 exec, exec, s[4:5]
	v_mov_b64_e32 v[92:93], v[120:121]
	v_mov_b64_e32 v[94:95], v[122:123]
	v_div_scale_f32 v96, s[4:5], v66, v66, 1.0
	v_div_scale_f32 v98, s[4:5], v82, v82, 1.0
	v_rcp_f32_e32 v104, v96
	v_div_scale_f32 v100, s[6:7], v84, v84, 1.0
	v_rcp_f32_e32 v105, v98
	v_div_scale_f32 v102, s[8:9], v86, v86, 1.0
	v_rcp_f32_e32 v106, v100
	v_rcp_f32_e32 v107, v102
	v_fma_f32 v108, -v96, v104, 1.0
	v_div_scale_f32 v97, vcc, 1.0, v66, 1.0
	v_fma_f32 v109, -v98, v105, 1.0
	v_fmac_f32_e32 v104, v108, v104
	v_div_scale_f32 v99, s[4:5], 1.0, v82, 1.0
	v_fma_f32 v110, -v100, v106, 1.0
	v_fmac_f32_e32 v105, v109, v105
	v_mul_f32_e32 v108, v97, v104
	v_div_scale_f32 v101, s[6:7], 1.0, v84, 1.0
	v_fma_f32 v111, -v102, v107, 1.0
	v_fmac_f32_e32 v106, v110, v106
	v_mul_f32_e32 v109, v99, v105
	v_fma_f32 v112, -v96, v108, v97
	v_div_scale_f32 v103, s[8:9], 1.0, v86, 1.0
	v_fmac_f32_e32 v107, v111, v107
	v_mul_f32_e32 v110, v101, v106
	v_fma_f32 v113, -v98, v109, v99
	v_fmac_f32_e32 v108, v112, v104
	v_mul_f32_e32 v111, v103, v107
	v_fma_f32 v114, -v100, v110, v101
	v_fmac_f32_e32 v109, v113, v105
	v_fma_f32 v96, -v96, v108, v97
	v_fma_f32 v115, -v102, v111, v103
	v_fmac_f32_e32 v110, v114, v106
	v_fma_f32 v97, -v98, v109, v99
	v_div_fmas_f32 v96, v96, v104, v108
	s_mov_b64 vcc, s[4:5]
	v_fmac_f32_e32 v111, v115, v107
	v_fma_f32 v98, -v100, v110, v101
	v_div_fixup_f32 v66, v96, v66, 1.0
	v_div_fmas_f32 v96, v97, v105, v109
	s_mov_b64 vcc, s[6:7]
	v_fma_f32 v99, -v102, v111, v103
	v_div_fixup_f32 v82, v96, v82, 1.0
	v_div_fmas_f32 v96, v98, v106, v110
	s_mov_b64 vcc, s[8:9]
	v_div_fixup_f32 v84, v96, v84, 1.0
	v_div_fmas_f32 v96, v99, v107, v111
	v_div_fixup_f32 v86, v96, v86, 1.0
	v_pk_mul_f32 v[192:193], v[192:193], v[86:87] op_sel_hi:[1,0]
	v_pk_mul_f32 v[194:195], v[194:195], v[86:87] op_sel_hi:[1,0]
	v_lshl_add_u64 v[80:81], s[52:53], 0, v[72:73]
	v_pk_mul_f32 v[206:207], v[206:207], v[84:85] op_sel_hi:[1,0]
	v_add_co_u32_e64 v80, s[10:11], s63, v80
	v_pk_mul_f32 v[208:209], v[208:209], v[84:85] op_sel_hi:[1,0]
	s_nop 0
	v_addc_co_u32_e64 v81, s[10:11], 0, v81, s[10:11]
	v_pk_mul_f32 v[188:189], v[188:189], v[82:83] op_sel_hi:[1,0]
	v_pk_mul_f32 v[190:191], v[190:191], v[82:83] op_sel_hi:[1,0]
	v_pk_mul_f32 v[184:185], v[184:185], v[66:67] op_sel_hi:[1,0]
	v_pk_mul_f32 v[186:187], v[186:187], v[66:67] op_sel_hi:[1,0]
	v_pk_mul_f32 v[172:173], v[172:173], v[86:87] op_sel_hi:[1,0]
	v_pk_mul_f32 v[174:175], v[174:175], v[86:87] op_sel_hi:[1,0]
	v_pk_mul_f32 v[176:177], v[176:177], v[84:85] op_sel_hi:[1,0]
	v_pk_mul_f32 v[178:179], v[178:179], v[84:85] op_sel_hi:[1,0]
	v_pk_mul_f32 v[180:181], v[180:181], v[82:83] op_sel_hi:[1,0]
	v_pk_mul_f32 v[182:183], v[182:183], v[82:83] op_sel_hi:[1,0]
	v_pk_mul_f32 v[168:169], v[168:169], v[66:67] op_sel_hi:[1,0]
	v_pk_mul_f32 v[170:171], v[170:171], v[66:67] op_sel_hi:[1,0]
	v_pk_mul_f32 v[152:153], v[152:153], v[86:87] op_sel_hi:[1,0]
	v_pk_mul_f32 v[154:155], v[154:155], v[86:87] op_sel_hi:[1,0]
	v_pk_mul_f32 v[164:165], v[164:165], v[66:67] op_sel_hi:[1,0]
	v_pk_mul_f32 v[194:195], v[194:195], v[94:95]
	v_pk_mul_f32 v[192:193], v[192:193], v[92:93]
	v_bfe_u32 v98, v194, 16, 1
	v_bfe_u32 v96, v192, 16, 1
	v_bfe_u32 v97, v193, 16, 1
	v_bfe_u32 v99, v195, 16, 1
	v_add3_u32 v192, v192, v96, s19
	v_add3_u32 v194, v194, v98, s19
	v_pk_mul_f32 v[206:207], v[206:207], v[92:93]
	v_add3_u32 v193, v193, v97, s19
	v_add3_u32 v195, v195, v99, s19
	v_lshrrev_b32_e32 v192, 16, v192
	v_lshrrev_b32_e32 v194, 16, v194
	v_bfe_u32 v100, v206, 16, 1
	v_and_or_b32 v192, v193, s62, v192
	v_and_or_b32 v193, v195, s62, v194
	v_add3_u32 v206, v206, v100, s19
	global_store_dwordx2 v[80:81], v[192:193], off
	v_bfe_u32 v192, v207, 16, 1
	v_pk_mul_f32 v[208:209], v[208:209], v[94:95]
	v_lshrrev_b32_e32 v206, 16, v206
	v_add3_u32 v192, v207, v192, s19
	v_and_or_b32 v194, v192, s62, v206
	v_bfe_u32 v192, v208, 16, 1
	v_add3_u32 v192, v208, v192, s19
	v_bfe_u32 v193, v209, 16, 1
	v_lshrrev_b32_e32 v192, 16, v192
	v_add3_u32 v193, v209, v193, s19
	v_and_or_b32 v195, v193, s62, v192
	v_lshl_add_u64 v[192:193], s[52:53], 0, v[74:75]
	v_pk_mul_f32 v[188:189], v[188:189], v[92:93]
	global_store_dwordx2 v[192:193], v[194:195], off offset:-1024
	v_bfe_u32 v194, v188, 16, 1
	v_add3_u32 v188, v188, v194, s19
	v_bfe_u32 v194, v189, 16, 1
	v_pk_mul_f32 v[190:191], v[190:191], v[94:95]
	v_lshrrev_b32_e32 v188, 16, v188
	v_add3_u32 v189, v189, v194, s19
	v_and_or_b32 v194, v189, s62, v188
	v_bfe_u32 v188, v190, 16, 1
	v_pk_mul_f32 v[184:185], v[184:185], v[92:93]
	v_add3_u32 v188, v190, v188, s19
	v_bfe_u32 v190, v184, 16, 1
	v_add3_u32 v184, v184, v190, s19
	v_bfe_u32 v190, v185, 16, 1
	v_pk_mul_f32 v[186:187], v[186:187], v[94:95]
	v_lshrrev_b32_e32 v184, 16, v184
	v_add3_u32 v185, v185, v190, s19
	v_and_or_b32 v190, v185, s62, v184
	v_bfe_u32 v184, v186, 16, 1
	v_bfe_u32 v189, v191, 16, 1
	v_add3_u32 v184, v186, v184, s19
	v_bfe_u32 v185, v187, 16, 1
	v_lshrrev_b32_e32 v188, 16, v188
	v_add3_u32 v189, v191, v189, s19
	v_lshrrev_b32_e32 v184, 16, v184
	v_add3_u32 v185, v187, v185, s19
	v_and_or_b32 v195, v189, s62, v188
	v_lshl_add_u64 v[188:189], s[52:53], 0, v[76:77]
	v_and_or_b32 v191, v185, s62, v184
	v_lshl_add_u64 v[184:185], s[52:53], 0, v[78:79]
	global_store_dwordx2 v[188:189], v[194:195], off offset:-1024
	global_store_dwordx2 v[184:185], v[190:191], off offset:-1024
	s_nop 1
	v_mov_b64_e32 v[194:195], v[124:125]
	v_mov_b64_e32 v[206:207], v[126:127]
	v_pk_mul_f32 v[166:167], v[166:167], v[66:67] op_sel_hi:[1,0]
	v_pk_mul_f32 v[160:161], v[160:161], v[82:83] op_sel_hi:[1,0]
	v_pk_mul_f32 v[162:163], v[162:163], v[82:83] op_sel_hi:[1,0]
	v_pk_mul_f32 v[156:157], v[156:157], v[84:85] op_sel_hi:[1,0]
	v_pk_mul_f32 v[158:159], v[158:159], v[84:85] op_sel_hi:[1,0]
	s_add_i32 s12, s12, s18
	s_add_u32 s46, s46, s28
	s_addc_u32 s47, s47, s29
	s_add_u32 s48, s48, s28
	v_pk_mul_f32 v[136:137], v[136:137], v[86:87] op_sel_hi:[1,0]
	v_pk_mul_f32 v[138:139], v[138:139], v[86:87] op_sel_hi:[1,0]
	s_addc_u32 s49, s49, s29
	v_pk_mul_f32 v[148:149], v[148:149], v[66:67] op_sel_hi:[1,0]
	v_pk_mul_f32 v[150:151], v[150:151], v[66:67] op_sel_hi:[1,0]
	v_pk_mul_f32 v[144:145], v[144:145], v[82:83] op_sel_hi:[1,0]
	v_pk_mul_f32 v[146:147], v[146:147], v[82:83] op_sel_hi:[1,0]
	v_pk_mul_f32 v[140:141], v[140:141], v[84:85] op_sel_hi:[1,0]
	v_pk_mul_f32 v[142:143], v[142:143], v[84:85] op_sel_hi:[1,0]
	s_add_u32 s56, s56, s28
	s_addc_u32 s57, s57, s29
	s_add_u32 s60, s60, s28
	s_addc_u32 s61, s61, s29
	v_lshl_add_u64 v[70:71], v[70:71], 0, s[36:37]
	v_lshl_add_u64 v[72:73], v[72:73], 0, s[44:45]
	v_lshl_add_u64 v[74:75], v[74:75], 0, s[44:45]
	v_lshl_add_u64 v[76:77], v[76:77], 0, s[44:45]
	s_cmpk_gt_i32 s12, 0x3fff
	v_lshl_add_u64 v[78:79], v[78:79], 0, s[44:45]
	v_pk_mul_f32 v[174:175], v[174:175], v[206:207]
	v_pk_mul_f32 v[172:173], v[172:173], v[194:195]
	v_pk_mul_f32 v[178:179], v[178:179], v[206:207]
	v_pk_mul_f32 v[176:177], v[176:177], v[194:195]
	v_bfe_u32 v186, v172, 16, 1
	v_bfe_u32 v190, v174, 16, 1
	v_bfe_u32 v187, v173, 16, 1
	v_bfe_u32 v191, v175, 16, 1
	v_bfe_u32 v208, v176, 16, 1
	v_bfe_u32 v92, v178, 16, 1
	v_add3_u32 v172, v172, v186, s19
	v_add3_u32 v174, v174, v190, s19
	v_bfe_u32 v209, v177, 16, 1
	v_bfe_u32 v93, v179, 16, 1
	v_add3_u32 v173, v173, v187, s19
	v_add3_u32 v175, v175, v191, s19
	v_add3_u32 v176, v176, v208, s19
	v_add3_u32 v178, v178, v92, s19
	v_lshrrev_b32_e32 v172, 16, v172
	v_lshrrev_b32_e32 v174, 16, v174
	v_pk_mul_f32 v[180:181], v[180:181], v[194:195]
	v_add3_u32 v177, v177, v209, s19
	v_add3_u32 v179, v179, v93, s19
	v_lshrrev_b32_e32 v176, 16, v176
	v_lshrrev_b32_e32 v178, 16, v178
	v_and_or_b32 v172, v173, s62, v172
	v_and_or_b32 v173, v175, s62, v174
	v_and_or_b32 v174, v177, s62, v176
	v_and_or_b32 v175, v179, s62, v178
	global_store_dwordx2 v[80:81], v[172:173], off offset:512
	global_store_dwordx2 v[192:193], v[174:175], off offset:-512
	v_bfe_u32 v172, v180, 16, 1
	v_add3_u32 v172, v180, v172, s19
	v_bfe_u32 v173, v181, 16, 1
	v_pk_mul_f32 v[182:183], v[182:183], v[206:207]
	v_lshrrev_b32_e32 v172, 16, v172
	v_add3_u32 v173, v181, v173, s19
	v_and_or_b32 v172, v173, s62, v172
	v_bfe_u32 v173, v182, 16, 1
	v_add3_u32 v173, v182, v173, s19
	v_bfe_u32 v174, v183, 16, 1
	v_lshrrev_b32_e32 v173, 16, v173
	v_add3_u32 v174, v183, v174, s19
	v_and_or_b32 v173, v174, s62, v173
	v_pk_mul_f32 v[168:169], v[168:169], v[194:195]
	global_store_dwordx2 v[188:189], v[172:173], off offset:-512
	v_bfe_u32 v172, v168, 16, 1
	v_add3_u32 v168, v168, v172, s19
	v_bfe_u32 v172, v169, 16, 1
	v_pk_mul_f32 v[170:171], v[170:171], v[206:207]
	v_lshrrev_b32_e32 v168, 16, v168
	v_add3_u32 v169, v169, v172, s19
	v_and_or_b32 v168, v169, s62, v168
	v_bfe_u32 v169, v170, 16, 1
	v_add3_u32 v169, v170, v169, s19
	v_bfe_u32 v170, v171, 16, 1
	v_lshrrev_b32_e32 v169, 16, v169
	v_add3_u32 v170, v171, v170, s19
	v_and_or_b32 v169, v170, s62, v169
	global_store_dwordx2 v[184:185], v[168:169], off offset:-512
	s_nop 1
	v_mov_b64_e32 v[168:169], v[128:129]
	v_mov_b64_e32 v[170:171], v[130:131]
	v_pk_mul_f32 v[154:155], v[154:155], v[170:171]
	v_pk_mul_f32 v[152:153], v[152:153], v[168:169]
	v_pk_mul_f32 v[158:159], v[158:159], v[170:171]
	v_pk_mul_f32 v[156:157], v[156:157], v[168:169]
	v_pk_mul_f32 v[162:163], v[162:163], v[170:171]
	v_pk_mul_f32 v[160:161], v[160:161], v[168:169]
	v_pk_mul_f32 v[166:167], v[166:167], v[170:171]
	v_pk_mul_f32 v[164:165], v[164:165], v[168:169]
	v_bfe_u32 v168, v152, 16, 1
	v_bfe_u32 v170, v154, 16, 1
	v_bfe_u32 v169, v153, 16, 1
	v_bfe_u32 v171, v155, 16, 1
	v_bfe_u32 v172, v156, 16, 1
	v_bfe_u32 v174, v158, 16, 1
	v_bfe_u32 v176, v160, 16, 1
	v_bfe_u32 v178, v162, 16, 1
	v_add3_u32 v152, v152, v168, s19
	v_add3_u32 v154, v154, v170, s19
	v_bfe_u32 v173, v157, 16, 1
	v_bfe_u32 v175, v159, 16, 1
	v_bfe_u32 v177, v161, 16, 1
	v_bfe_u32 v179, v163, 16, 1
	v_add3_u32 v153, v153, v169, s19
	v_add3_u32 v155, v155, v171, s19
	v_add3_u32 v156, v156, v172, s19
	v_add3_u32 v158, v158, v174, s19
	v_add3_u32 v160, v160, v176, s19
	v_add3_u32 v162, v162, v178, s19
	v_lshrrev_b32_e32 v152, 16, v152
	v_lshrrev_b32_e32 v154, 16, v154
	v_add3_u32 v157, v157, v173, s19
	v_add3_u32 v159, v159, v175, s19
	v_add3_u32 v161, v161, v177, s19
	v_add3_u32 v163, v163, v179, s19
	v_lshrrev_b32_e32 v156, 16, v156
	v_lshrrev_b32_e32 v158, 16, v158
	v_lshrrev_b32_e32 v160, 16, v160
	v_lshrrev_b32_e32 v162, 16, v162
	v_and_or_b32 v152, v153, s62, v152
	v_and_or_b32 v153, v155, s62, v154
	v_and_or_b32 v154, v157, s62, v156
	v_and_or_b32 v155, v159, s62, v158
	v_and_or_b32 v156, v161, s62, v160
	v_and_or_b32 v157, v163, s62, v162
	global_store_dwordx2 v[80:81], v[152:153], off offset:1024
	global_store_dwordx2 v[192:193], v[154:155], off
	global_store_dwordx2 v[188:189], v[156:157], off
	v_bfe_u32 v152, v164, 16, 1
	v_add3_u32 v152, v164, v152, s19
	v_bfe_u32 v153, v165, 16, 1
	v_lshrrev_b32_e32 v152, 16, v152
	v_add3_u32 v153, v165, v153, s19
	v_and_or_b32 v152, v153, s62, v152
	v_bfe_u32 v153, v166, 16, 1
	v_add3_u32 v153, v166, v153, s19
	v_bfe_u32 v154, v167, 16, 1
	v_lshrrev_b32_e32 v153, 16, v153
	v_add3_u32 v154, v167, v154, s19
	v_and_or_b32 v153, v154, s62, v153
	global_store_dwordx2 v[184:185], v[152:153], off
	s_nop 1
	v_mov_b64_e32 v[152:153], v[132:133]
	v_mov_b64_e32 v[154:155], v[134:135]
	v_pk_mul_f32 v[138:139], v[138:139], v[154:155]
	v_pk_mul_f32 v[136:137], v[136:137], v[152:153]
	v_pk_mul_f32 v[142:143], v[142:143], v[154:155]
	v_pk_mul_f32 v[140:141], v[140:141], v[152:153]
	v_pk_mul_f32 v[146:147], v[146:147], v[154:155]
	v_pk_mul_f32 v[144:145], v[144:145], v[152:153]
	v_pk_mul_f32 v[150:151], v[150:151], v[154:155]
	v_pk_mul_f32 v[148:149], v[148:149], v[152:153]
	v_bfe_u32 v152, v136, 16, 1
	v_bfe_u32 v154, v138, 16, 1
	v_bfe_u32 v153, v137, 16, 1
	v_bfe_u32 v155, v139, 16, 1
	v_bfe_u32 v156, v140, 16, 1
	v_bfe_u32 v158, v142, 16, 1
	v_bfe_u32 v160, v144, 16, 1
	v_bfe_u32 v162, v146, 16, 1
	v_bfe_u32 v164, v148, 16, 1
	v_bfe_u32 v166, v150, 16, 1
	v_add3_u32 v136, v136, v152, s19
	v_add3_u32 v138, v138, v154, s19
	v_bfe_u32 v157, v141, 16, 1
	v_bfe_u32 v159, v143, 16, 1
	v_bfe_u32 v161, v145, 16, 1
	v_bfe_u32 v163, v147, 16, 1
	v_bfe_u32 v165, v149, 16, 1
	v_bfe_u32 v167, v151, 16, 1
	v_add3_u32 v137, v137, v153, s19
	v_add3_u32 v139, v139, v155, s19
	v_add3_u32 v140, v140, v156, s19
	v_add3_u32 v142, v142, v158, s19
	v_add3_u32 v144, v144, v160, s19
	v_add3_u32 v146, v146, v162, s19
	v_add3_u32 v148, v148, v164, s19
	v_add3_u32 v150, v150, v166, s19
	v_lshrrev_b32_e32 v136, 16, v136
	v_lshrrev_b32_e32 v138, 16, v138
	v_add3_u32 v141, v141, v157, s19
	v_add3_u32 v143, v143, v159, s19
	v_add3_u32 v145, v145, v161, s19
	v_add3_u32 v147, v147, v163, s19
	v_add3_u32 v149, v149, v165, s19
	v_add3_u32 v151, v151, v167, s19
	v_lshrrev_b32_e32 v140, 16, v140
	v_lshrrev_b32_e32 v142, 16, v142
	v_lshrrev_b32_e32 v144, 16, v144
	v_lshrrev_b32_e32 v146, 16, v146
	v_lshrrev_b32_e32 v148, 16, v148
	v_lshrrev_b32_e32 v150, 16, v150
	v_and_or_b32 v136, v137, s62, v136
	v_and_or_b32 v137, v139, s62, v138
	v_and_or_b32 v138, v141, s62, v140
	v_and_or_b32 v139, v143, s62, v142
	v_and_or_b32 v140, v145, s62, v144
	v_and_or_b32 v141, v147, s62, v146
	v_and_or_b32 v142, v149, s62, v148
	v_and_or_b32 v143, v151, s62, v150
	global_store_dwordx2 v[80:81], v[136:137], off offset:1536
	global_store_dwordx2 v[192:193], v[138:139], off offset:512
	global_store_dwordx2 v[188:189], v[140:141], off offset:512
	global_store_dwordx2 v[184:185], v[142:143], off offset:512
	s_branch .LBB0_58
.LBB0_58:
	s_nop 0
	s_waitcnt lgkmcnt(0)
	s_cmp_lg_u32 s3, 0
	s_cselect_b64 s[46:47], -1, 0
	s_and_b64 vcc, exec, s[46:47]
	v_lshrrev_b32_e32 v202, 20, v0
	v_lshrrev_b32_e32 v203, 10, v0
	s_cbranch_vccz .LBB0_71
	v_or_b32_e32 v0, v203, v202
	s_movk_i32 s0, 0x3ff
	v_and_or_b32 v0, v0, s0, v196
	v_cmp_eq_u32_e32 vcc, 0, v0
	s_barrier
	s_and_saveexec_b64 s[0:1], vcc
	s_cbranch_execz .LBB0_69
	v_readlane_b32 s4, v242, 0
	v_readlane_b32 s5, v242, 1
	buffer_wbl2 sc1
	s_waitcnt vmcnt(0)
	s_load_dwordx2 s[4:5], s[4:5], 0x58
	v_mov_b32_e32 v2, 0
	s_mov_b64 s[6:7], exec
	v_mbcnt_lo_u32_b32 v1, s6, 0
	v_mbcnt_hi_u32_b32 v1, s7, v1
	s_waitcnt lgkmcnt(0)
	global_load_dword v0, v2, s[4:5] offset:40
	v_cmp_eq_u32_e32 vcc, 0, v1
	s_and_saveexec_b64 s[8:9], vcc
	s_cbranch_execz .LBB0_62
	s_bcnt1_i32_b64 s3, s[6:7]
	v_mov_b32_e32 v3, s3
	global_atomic_add v3, v2, v3, s[4:5] offset:32 sc0
